# adds: attention per-chunk vmcnt waits removed (Q fragments waited once at sb 0), so O-store drain and next-Q prefetch no longer stall each sub-block
# speedup vs baseline: 1.0001x; 1.0001x over previous
; #define LAS __attribute__((address_space(3)))
; __device__ __forceinline__ void attn_phase(LAS unsigned char* lds, const bf16_t* Q, const bf16_t* Kb, const bf16_t* Vt, bf16_t* AO, const float* sink, const float* qg, const float* kg) {
;     ...
;         for (int sb = 0; sb < 4; ++sb) {
;             const int q0 = sb * 32;
;             if (sb < 3) {
; #pragma unroll
;                 for (int s = 0; s < 4; ++s) qn[s] = *(const bf16x8*)(qbase + (size_t)(q0 + 32) * DM + 16 * s);
;             }
;             f32x16 o0, o1;
; #pragma unroll
;             for (int e = 0; e < 16; ++e) { o0[e] = 0.f; o1[e] = 0.f; }
;             float lrun = (h == 0) ? __builtin_amdgcn_exp2f(sk - MREF) : 0.f;
;             bf16x8 kf[4];
; #pragma unroll
;             for (int st = 0; st < 4; ++st) kf[st] = *(const LAS bf16x8*)(Kl + (q0 + r) * KROW + (16 * st + 8 * h) * 2);
;             for (int cc = 0; cc < 9; ++cc) {
;                 const int kw0 = q0 + 32 * cc, l0 = nb * 128 - 128 + kw0;
;                 const bool valid = (l0 >= 0 && l0 < SEQ);
;                 u32x2 vv[2][2][2]; bf16x8 kn[4];
; #pragma unroll
;                 for (int st = 0; st < 2; ++st)
; #pragma unroll
;                     for (int dt = 0; dt < 2; ++dt) { const LAS unsigned char* vp = Vl + (32 * dt + r) * VROW + (kw0 + 16 * st + 4 * h) * 2; vv[st][dt][0] = *(const LAS u32x2*)vp; vv[st][dt][1] = *(const LAS u32x2*)(vp + 16); }
;                 const int kwn = cc < 8 ? kw0 + 32 : kw0;
; #pragma unroll
;                 for (int st = 0; st < 4; ++st) kn[st] = *(const LAS bf16x8*)(Kl + (kwn + r) * KROW + (16 * st + 8 * h) * 2);
;                 __builtin_amdgcn_sched_barrier(0);
;                 if (valid) {
;                 f32x16 sc;
; #pragma unroll
;                 for (int e = 0; e < 16; ++e) sc[e] = -MREF;
; #pragma unroll
;                 for (int st = 0; st < 4; ++st) sc = __builtin_amdgcn_mfma_f32_32x32x16_bf16(kf[st], qf[st], sc, 0, 0, 0);
;                 if (cc == 0) {
; #pragma unroll
;                     for (int e = 0; e < 16; ++e) { const int kj = (e & 3) + 8 * (e >> 2) + 4 * h; if (kj < r) sc[e] = -INFINITY; }
;                 }
;                 if (cc == 8) {
; #pragma unroll
;                     for (int e = 0; e < 16; ++e) { const int kj = (e & 3) + 8 * (e >> 2) + 4 * h; if (kj > r) sc[e] = -INFINITY; }
;                 }
;                 float ps = 0.f;
; #pragma unroll
.LBB0_177:
	s_lshl_b32 s26, s14, 5
	v_or_b32_e32 v0, s26, v214
	s_lshl_b32 s12, s14, 6
	v_mad_u64_u32 v[2:3], s[16:17], v0, s18, v[198:199]
	v_add3_u32 v0, v245, s12, v244
	v_add_u32_e32 v6, 0xd800, v0
	v_add_u32_e32 v0, 0xd820, v0
	ds_read_b128 v[60:63], v2
	ds_read_b128 v[56:59], v2 offset:32
	ds_read_b128 v[52:55], v2 offset:64
	ds_read_b128 v[48:51], v2 offset:96
	ds_read2_b64 v[10:13], v6 offset1:2
	ds_read2_b64 v[2:5], v6 offset0:4 offset1:6
	v_add_u32_e32 v6, 0x6000, v6
	v_add_u32_e32 v0, 0x6000, v0
	ds_read2_b64 v[64:67], v6 offset0:32 offset1:34
	ds_read2_b64 v[6:9], v0 offset0:32 offset1:34
	v_or_b32_e32 v0, 32, v214
	v_add_u32_e32 v0, s26, v0
	v_mad_u64_u32 v[14:15], s[16:17], v0, s18, v[198:199]
	ds_read_b128 v[80:83], v14
	ds_read_b128 v[84:87], v14 offset:32
	ds_read_b128 v[88:91], v14 offset:64
	ds_read_b128 v[92:95], v14 offset:96
	s_cmp_lg_u32 s14, 0
	s_cbranch_scc1 .Lattn_novm
	s_waitcnt vmcnt(4)
.Lattn_novm:
	s_add_i32 s12, s26, s40
	s_cmpk_gt_u32 s12, 0xfff
	s_cbranch_scc1 .LBB0_179
	s_waitcnt lgkmcnt(11)
	v_mfma_f32_32x32x16_bf16 v[32:47], v[60:63], v[188:191], v[16:31]
	s_waitcnt lgkmcnt(10)
	v_mfma_f32_32x32x16_bf16 v[32:47], v[56:59], v[184:187], v[32:47]
	s_waitcnt lgkmcnt(9)
	v_mfma_f32_32x32x16_bf16 v[32:47], v[52:55], v[180:183], v[32:47]
	s_waitcnt lgkmcnt(8)
	v_mfma_f32_32x32x16_bf16 v[32:47], v[48:51], v[176:179], v[32:47]
	s_nop 11
	v_cndmask_b32_e64 v0, v32, v235, s[38:39]
	v_cndmask_b32_e64 v14, v33, v235, s[42:43]
	v_exp_f32_e32 v0, v0
	v_cndmask_b32_e64 v15, v34, v235, s[44:45]
	v_exp_f32_e32 v14, v14
	v_cndmask_b32_e64 v32, v35, v235, s[46:47]
	v_exp_f32_e32 v15, v15
	v_cndmask_b32_e64 v33, v36, v235, s[48:49]
	v_cndmask_b32_e64 v34, v37, v235, s[50:51]
	v_cndmask_b32_e64 v35, v38, v235, s[52:53]
	v_cndmask_b32_e64 v36, v39, v235, s[54:55]
	v_exp_f32_e32 v68, v32
	v_cndmask_b32_e64 v37, v40, v235, s[56:57]
	v_cndmask_b32_e64 v38, v41, v235, s[58:59]
	v_cndmask_b32_e64 v39, v42, v235, s[60:61]
	v_cndmask_b32_e64 v40, v43, v235, s[62:63]
	v_cndmask_b32_e64 v41, v44, v235, s[64:65]
	v_cndmask_b32_e64 v42, v45, v235, s[66:67]
	v_cndmask_b32_e64 v43, v46, v235, s[68:69]
	v_cndmask_b32_e64 v44, v47, v235, s[70:71]
	v_exp_f32_e32 v69, v33
	v_exp_f32_e32 v70, v34
	v_exp_f32_e32 v71, v35
	v_exp_f32_e32 v72, v36
	v_cvt_pk_bf16_f32 v32, v0, v14
	v_cvt_pk_bf16_f32 v33, v15, v68
	v_cvt_pk_bf16_f32 v34, v69, v70
	v_cvt_pk_bf16_f32 v35, v71, v72
	v_add_f32_e32 v0, 0, v0
	v_exp_f32_e32 v73, v37
	v_exp_f32_e32 v74, v38
	v_exp_f32_e32 v75, v39
	v_exp_f32_e32 v76, v40
	v_exp_f32_e32 v77, v41
	v_exp_f32_e32 v78, v42
	v_exp_f32_e32 v79, v43
	v_exp_f32_e32 v96, v44
	s_waitcnt lgkmcnt(7)
	v_mfma_f32_32x32x16_bf16 v[48:63], v[10:13], v[32:35], 0
	v_add_f32_e32 v0, v14, v0
	v_add_f32_e32 v0, v15, v0
	v_add_f32_e32 v0, v68, v0
	v_add_f32_e32 v0, v69, v0
	v_add_f32_e32 v0, v70, v0
	v_add_f32_e32 v0, v71, v0
	v_add_f32_e32 v0, v72, v0
	s_waitcnt lgkmcnt(5)
	v_mfma_f32_32x32x16_bf16 v[32:47], v[64:67], v[32:35], 0
	v_add_f32_e32 v0, v73, v0
	v_cvt_pk_bf16_f32 v10, v73, v74
	v_cvt_pk_bf16_f32 v11, v75, v76
	v_cvt_pk_bf16_f32 v12, v77, v78
	v_cvt_pk_bf16_f32 v13, v79, v96
	v_add_f32_e32 v0, v74, v0
	v_add_f32_e32 v0, v75, v0
	v_mfma_f32_32x32x16_bf16 v[48:63], v[2:5], v[10:13], v[48:63]
	v_add_f32_e32 v0, v76, v0
	v_add_f32_e32 v0, v77, v0
	v_add_f32_e32 v0, v78, v0
	v_add_f32_e32 v0, v79, v0
	v_add_f32_e32 v0, v96, v0
	v_add_f32_e32 v209, v207, v0
	s_waitcnt lgkmcnt(4)
	v_mfma_f32_32x32x16_bf16 v[32:47], v[6:9], v[10:13], v[32:47]
	s_branch .LBB0_180

; #define LAS __attribute__((address_space(3)))
; __device__ __forceinline__ void attn_phase(LAS unsigned char* lds, const bf16_t* Q, const bf16_t* Kb, const bf16_t* Vt, bf16_t* AO, const float* sink, const float* qg, const float* kg) {
;     ...
;             for (int cc = 0; cc < 9; ++cc) {
;                 const int kw0 = q0 + 32 * cc, l0 = nb * 128 - 128 + kw0;
;                 const bool valid = (l0 >= 0 && l0 < SEQ);
;                 u32x2 vv[2][2][2]; bf16x8 kn[4];
; #pragma unroll
;                 for (int st = 0; st < 2; ++st)
; #pragma unroll
;                     for (int dt = 0; dt < 2; ++dt) { const LAS unsigned char* vp = Vl + (32 * dt + r) * VROW + (kw0 + 16 * st + 4 * h) * 2; vv[st][dt][0] = *(const LAS u32x2*)vp; vv[st][dt][1] = *(const LAS u32x2*)(vp + 16); }
;                 const int kwn = cc < 8 ? kw0 + 32 : kw0;
; #pragma unroll
;                 for (int st = 0; st < 4; ++st) kn[st] = *(const LAS bf16x8*)(Kl + (kwn + r) * KROW + (16 * st + 8 * h) * 2);
;                 __builtin_amdgcn_sched_barrier(0);
;                 if (valid) {
;                 f32x16 sc;
; #pragma unroll
;                 for (int e = 0; e < 16; ++e) sc[e] = -MREF;
; #pragma unroll
;                 for (int st = 0; st < 4; ++st) sc = __builtin_amdgcn_mfma_f32_32x32x16_bf16(kf[st], qf[st], sc, 0, 0, 0);
;                 if (cc == 0) {
; #pragma unroll
;                     for (int e = 0; e < 16; ++e) { const int kj = (e & 3) + 8 * (e >> 2) + 4 * h; if (kj < r) sc[e] = -INFINITY; }
;                 }
;                 if (cc == 8) {
; #pragma unroll
;                     for (int e = 0; e < 16; ++e) { const int kj = (e & 3) + 8 * (e >> 2) + 4 * h; if (kj > r) sc[e] = -INFINITY; }
.LBB0_181:
	s_add_i32 s0, s17, 0x80
	s_add_i32 s1, s15, s17
	s_add_i32 s30, s17, 0xa0
	s_cmpk_eq_i32 s16, 0x1c0
	s_cselect_b64 vcc, -1, 0
	v_add_u32_e32 v0, s16, v246
	s_and_b64 s[12:13], vcc, exec
	v_add_u32_e32 v2, 0xd800, v0
	v_add_u32_e32 v6, 0x13940, v0
	s_cselect_b32 s0, s0, s30
	ds_read2_b64 v[192:195], v2 offset0:8 offset1:10
	ds_read2_b64 v[2:5], v2 offset0:12 offset1:14
	ds_read_b64 v[10:11], v6
	ds_read_b64 v[12:13], v6 offset:16
	ds_read_b64 v[8:9], v6 offset:48
	ds_read_b64 v[6:7], v6 offset:32
	v_or_b32_e32 v0, s0, v214
	v_mad_u32_u24 v14, v0, s18, v198
	ds_read_b128 v[64:67], v14
	ds_read_b128 v[68:71], v14 offset:32
	ds_read_b128 v[72:75], v14 offset:64
	ds_read_b128 v[76:79], v14 offset:96
	s_cmpk_gt_u32 s1, 0xfff
	s_cbranch_scc1 .LBB0_185
	s_waitcnt lgkmcnt(13)
	v_mfma_f32_32x32x16_bf16 v[96:111], v[80:83], v[188:191], v[16:31]
	s_andn2_b64 vcc, exec, vcc
	s_waitcnt lgkmcnt(12)
	v_mfma_f32_32x32x16_bf16 v[96:111], v[84:87], v[184:187], v[96:111]
	s_waitcnt lgkmcnt(11)
	v_mfma_f32_32x32x16_bf16 v[96:111], v[88:91], v[180:183], v[96:111]
	s_waitcnt lgkmcnt(10)
	v_mfma_f32_32x32x16_bf16 v[96:111], v[92:95], v[176:179], v[96:111]
	s_cbranch_vccnz .LBB0_184
	s_nop 10
	v_cndmask_b32_e64 v0, v96, v235, s[72:73]
	v_cndmask_b32_e64 v97, v235, v97, s[38:39]
	v_cndmask_b32_e64 v96, v0, v96, s[38:39]
	v_cndmask_b32_e64 v98, v98, v235, s[74:75]
	v_cndmask_b32_e64 v99, v99, v235, s[76:77]
	v_cndmask_b32_e64 v100, v100, v235, s[78:79]
	v_cndmask_b32_e64 v101, v101, v235, s[80:81]
	v_cndmask_b32_e64 v102, v102, v235, s[82:83]
	v_cndmask_b32_e64 v103, v103, v235, s[84:85]
	v_cndmask_b32_e64 v104, v104, v235, s[86:87]
	v_cndmask_b32_e64 v105, v105, v235, s[88:89]
	v_cndmask_b32_e64 v106, v106, v235, s[90:91]
	v_cndmask_b32_e64 v107, v107, v235, s[92:93]
	v_cndmask_b32_e64 v108, v108, v235, s[94:95]
	v_cndmask_b32_e64 v109, v109, v235, s[96:97]
	v_cndmask_b32_e64 v110, v110, v235, s[36:37]
	v_cndmask_b32_e64 v111, v111, v235, s[4:5]

; #define LAS __attribute__((address_space(3)))
; __device__ __forceinline__ void attn_phase(LAS unsigned char* lds, const bf16_t* Q, const bf16_t* Kb, const bf16_t* Vt, bf16_t* AO, const float* sink, const float* qg, const float* kg) {
;     ...
;             for (int cc = 0; cc < 9; ++cc) {
;                 const int kw0 = q0 + 32 * cc, l0 = nb * 128 - 128 + kw0;
;                 const bool valid = (l0 >= 0 && l0 < SEQ);
;                 u32x2 vv[2][2][2]; bf16x8 kn[4];
; #pragma unroll
;                 for (int st = 0; st < 2; ++st)
; #pragma unroll
;                     for (int dt = 0; dt < 2; ++dt) { const LAS unsigned char* vp = Vl + (32 * dt + r) * VROW + (kw0 + 16 * st + 4 * h) * 2; vv[st][dt][0] = *(const LAS u32x2*)vp; vv[st][dt][1] = *(const LAS u32x2*)(vp + 16); }
;                 const int kwn = cc < 8 ? kw0 + 32 : kw0;
; #pragma unroll
;                 for (int st = 0; st < 4; ++st) kn[st] = *(const LAS bf16x8*)(Kl + (kwn + r) * KROW + (16 * st + 8 * h) * 2);
;                 __builtin_amdgcn_sched_barrier(0);
;                 if (valid) {
;                 f32x16 sc;
; #pragma unroll
;                 for (int e = 0; e < 16; ++e) sc[e] = -MREF;
; #pragma unroll
;                 for (int st = 0; st < 4; ++st) sc = __builtin_amdgcn_mfma_f32_32x32x16_bf16(kf[st], qf[st], sc, 0, 0, 0);
;                 if (cc == 0) {
; #pragma unroll
;                     for (int e = 0; e < 16; ++e) { const int kj = (e & 3) + 8 * (e >> 2) + 4 * h; if (kj < r) sc[e] = -INFINITY; }
;                 }
;                 if (cc == 8) {
; #pragma unroll
;                     for (int e = 0; e < 16; ++e) { const int kj = (e & 3) + 8 * (e >> 2) + 4 * h; if (kj > r) sc[e] = -INFINITY; }
.LBB0_185:
	s_add_i32 s16, s16, 64
	s_add_i32 s17, s17, 32
	s_cmpk_eq_i32 s16, 0x200
	s_cbranch_scc1 .LBB0_187
	s_waitcnt lgkmcnt(0)
	s_add_i32 s0, s17, 0x80
	s_add_i32 s1, s15, s17
	s_add_i32 s30, s17, 0xa0
	s_cmpk_eq_i32 s16, 0x1c0
	s_cselect_b64 vcc, -1, 0
	v_add_u32_e32 v0, s16, v246
	s_and_b64 s[12:13], vcc, exec
	v_add_u32_e32 v2, 0xd800, v0
	v_add_u32_e32 v6, 0x13940, v0
	s_cselect_b32 s0, s0, s30
	ds_read2_b64 v[192:195], v2 offset0:8 offset1:10
	ds_read2_b64 v[2:5], v2 offset0:12 offset1:14
	ds_read_b64 v[10:11], v6
	ds_read_b64 v[12:13], v6 offset:16
	ds_read_b64 v[8:9], v6 offset:48
	ds_read_b64 v[6:7], v6 offset:32
	v_or_b32_e32 v0, s0, v214
	v_mad_u32_u24 v14, v0, s18, v198
	ds_read_b128 v[80:83], v14
	ds_read_b128 v[84:87], v14 offset:32
	ds_read_b128 v[88:91], v14 offset:64
	ds_read_b128 v[92:95], v14 offset:96
	s_cmpk_gt_u32 s1, 0xfff
	s_cbranch_scc1 .Lattn_185b
	s_waitcnt lgkmcnt(13)
	v_mfma_f32_32x32x16_bf16 v[96:111], v[64:67], v[188:191], v[16:31]
	s_andn2_b64 vcc, exec, vcc
	s_waitcnt lgkmcnt(12)
	v_mfma_f32_32x32x16_bf16 v[96:111], v[68:71], v[184:187], v[96:111]
	s_waitcnt lgkmcnt(11)
	v_mfma_f32_32x32x16_bf16 v[96:111], v[72:75], v[180:183], v[96:111]
	s_waitcnt lgkmcnt(10)
	v_mfma_f32_32x32x16_bf16 v[96:111], v[76:79], v[176:179], v[96:111]
	s_cbranch_vccnz .Lattn_184b
	s_nop 10
	v_cndmask_b32_e64 v0, v96, v235, s[72:73]
	v_cndmask_b32_e64 v97, v235, v97, s[38:39]
	v_cndmask_b32_e64 v96, v0, v96, s[38:39]
	v_cndmask_b32_e64 v98, v98, v235, s[74:75]
	v_cndmask_b32_e64 v99, v99, v235, s[76:77]
	v_cndmask_b32_e64 v100, v100, v235, s[78:79]
	v_cndmask_b32_e64 v101, v101, v235, s[80:81]
	v_cndmask_b32_e64 v102, v102, v235, s[82:83]
	v_cndmask_b32_e64 v103, v103, v235, s[84:85]
	v_cndmask_b32_e64 v104, v104, v235, s[86:87]
	v_cndmask_b32_e64 v105, v105, v235, s[88:89]
	v_cndmask_b32_e64 v106, v106, v235, s[90:91]
	v_cndmask_b32_e64 v107, v107, v235, s[92:93]
	v_cndmask_b32_e64 v108, v108, v235, s[94:95]
	v_cndmask_b32_e64 v109, v109, v235, s[96:97]
	v_cndmask_b32_e64 v110, v110, v235, s[36:37]
	v_cndmask_b32_e64 v111, v111, v235, s[4:5]
